# NSA selected branch on 16x16x32 MFMA tiles: each wave skips 2-token groups that did not select the block (vsT key permutation follows the new operand layout)
# speedup vs baseline: 1.0110x; 1.0110x over previous
.LBB0_847:
	s_add_u32 s2, s34, 0x10724000
	v_writelane_b32 v231, s2, 14
	s_addc_u32 s2, s35, 0
	s_add_u32 s52, s34, 0x10f24000
	s_addc_u32 s53, s35, 0
	v_writelane_b32 v231, s2, 10
	s_add_u32 s2, s34, 0x11724000
	v_writelane_b32 v231, s2, 26
	s_addc_u32 s2, s35, 0
	v_writelane_b32 v231, s2, 27
	s_add_u32 s2, s34, 0x11f24000
	s_addc_u32 s3, s35, 0
	v_writelane_b32 v231, s2, 28
	s_nop 1
	v_writelane_b32 v231, s3, 29
	s_add_u32 s2, s34, 0x12724000
	s_addc_u32 s3, s35, 0
	s_cmp_lt_i32 s6, 8
	v_writelane_b32 v231, s2, 30
	s_cselect_b64 s[14:15], -1, 0
	s_nop 0
	v_writelane_b32 v231, s3, 31
	s_and_b64 s[2:3], s[14:15], s[4:5]
	s_andn2_b64 vcc, exec, s[2:3]
	s_cbranch_vccnz .LBB0_1021
	s_load_dword s2, s[0:1], 0x100
	s_waitcnt lgkmcnt(0)
	s_lshr_b32 s19, s2, 3
	s_cmpk_gt_u32 s85, 0x5ff
	s_cbranch_scc1 .LBB0_941
	v_lshlrev_b32_e32 v3, 3, v166
	v_add_u32_e32 v5, 0x800, v3
	v_and_b32_e32 v2, 56, v3
	v_and_b32_e32 v4, 0x1fc0, v3
	v_and_b32_e32 v6, 0x3fc0, v5
	v_add_u32_e32 v5, 0x1000, v3
	v_add_u32_e32 v3, 0x1800, v3
	v_and_b32_e32 v10, 0x3fc0, v3
	v_lshrrev_b32_e32 v3, 3, v166
	v_lshlrev_b32_e32 v12, 1, v2
	v_mul_u32_u24_e32 v3, 0x48, v3
	v_lshl_add_u32 v105, v3, 1, v12
	v_add_u32_e32 v3, 0x100, v166
	v_lshrrev_b32_e32 v3, 3, v3
	v_mul_u32_u24_e32 v3, 0x48, v3
	v_lshl_add_u32 v109, v3, 1, v12
	v_add_u32_e32 v3, 0x200, v166
	v_lshrrev_b32_e32 v3, 3, v3
	v_mul_u32_u24_e32 v3, 0x48, v3
	v_lshl_add_u32 v111, v3, 1, v12
	v_add_u32_e32 v3, 0x300, v166
	v_lshrrev_b32_e32 v3, 3, v3
	v_readlane_b32 s4, v231, 2
	v_mul_u32_u24_e32 v3, 0x48, v3
	v_and_b32_e32 v1, 31, v166
	v_bfe_u32 v103, v166, 6, 1
	s_waitcnt vmcnt(8)
	v_lshlrev_b32_e32 v98, 4, v166
	v_mov_b32_e32 v99, 0
	v_readlane_b32 s5, v231, 3
	v_lshl_add_u32 v167, v3, 1, v12
	v_bfe_u32 v3, v166, 5, 1
	v_lshl_add_u64 v[100:101], s[4:5], 0, v[98:99]
	v_and_b32_e32 v8, 0x3fc0, v5
	v_lshl_or_b32 v5, v103, 6, v1
	v_lshlrev_b32_e32 v98, 4, v3
	v_lshrrev_b32_e32 v7, 1, v166
	s_movk_i32 s4, 0x90
	s_lshl_b32 s3, s85, 5
	v_and_b32_e32 v168, 0x1c0, v7
	v_mul_u32_u24_e32 v11, 0x90, v5
	v_mad_u32_u24 v169, v5, s4, v98
	v_lshlrev_b32_e32 v5, 1, v166
	s_lshr_b32 s2, s85, 3
	s_and_b32 s3, s3, 0xe0
	v_or_b32_e32 v9, v168, v1
	v_and_b32_e32 v5, 8, v5
	v_mul_u32_u24_e32 v14, 0x90, v9
	v_mad_u32_u24 v170, v9, s4, v98
	v_and_or_b32 v5, v7, 4, v5
	s_getpc_b64 s[4:5]
	s_add_u32 s4, s4, _ZL8ROPE_INV@rel32@lo+4
	s_addc_u32 s5, s5, _ZL8ROPE_INV@rel32@hi+12
	v_and_or_b32 v171, v166, 63, 32
	v_mov_b32_e32 v13, v99
	v_lshlrev_b32_e32 v122, 1, v2
	v_mbcnt_lo_u32_b32 v2, -1, 0
	s_movk_i32 s13, 0x1000
	v_lshlrev_b32_e32 v102, 8, v3
	v_lshlrev_b32_e32 v104, 2, v3
	v_lshl_add_u64 v[106:107], s[4:5], 0, v[98:99]
	v_and_or_b32 v108, v166, 19, v5
	v_and_or_b32 v110, v171, 51, v5
	v_and_b32_e32 v214, 12, v166
	v_lshlrev_b32_e32 v214, 1, v214
	v_bfe_u32 v215, v166, 4, 1
	v_lshl_or_b32 v214, v215, 2, v214
	v_and_or_b32 v214, v166, 3, v214
	v_or_b32_e32 v215, 32, v214
	v_lshl_add_u64 v[112:113], s[92:93], 0, v[12:13]
	s_mov_b32 s11, 0
	v_lshlrev_b32_e32 v114, 1, v4
	v_mov_b32_e32 v115, v99
	v_lshlrev_b32_e32 v116, 1, v6
	v_mov_b32_e32 v117, v99
	v_lshlrev_b32_e32 v118, 1, v8
	v_mov_b32_e32 v119, v99
	v_lshlrev_b32_e32 v120, 1, v10
	v_mov_b32_e32 v121, v99
	v_mov_b32_e32 v123, v99
	v_add_u32_e32 v172, v98, v11
	v_add_u32_e32 v173, v98, v14
	v_mov_b32_e32 v174, 0x358637bd
	s_mov_b32 s17, 0x800000
	s_brev_b32 s20, 18
	s_mov_b32 s21, 0xfe5163ab
	s_mov_b32 s23, 0x3c439041
	s_mov_b32 s24, 0xdb629599
	s_mov_b32 s25, 0xf534ddc0
	s_mov_b32 s28, 0xfc2757d1
	s_mov_b32 s29, 0x4e441529
	s_mov_b32 s33, 0xa2f9836e
	s_mov_b32 s50, 0x3fc90fda
	s_mov_b32 s51, 0x3f22f983
	s_mov_b32 s61, 0xbfc90fda
	s_movk_i32 s63, 0x1f8
	v_mbcnt_hi_u32_b32 v175, -1, v2
	v_not_b32_e32 v176, 63
	v_not_b32_e32 v177, 31
	v_mov_b32_e32 v178, 0x7fc00000
	s_mov_b32 s65, s2
	s_mov_b32 s12, 0x3c0881c4
	s_mov_b32 s16, 0xb94c1982
	s_mov_b32 s18, 0xbab64f3b
	s_mov_b32 s22, 0x37d75334
	s_mov_b32 s60, 0x3d2aabf7
	s_mov_b32 s62, 0xbf000004
	s_mov_b32 s64, 0xbe2aaa9d
	s_branch .LBB0_851

.LBB0_857:
	s_mov_b64 s[4:5], 0
	s_cbranch_execz .LBB0_859
	v_lshlrev_b32_e32 v70, 7, v180
	v_lshl_add_u64 v[68:69], s[52:53], 0, v[98:99]
	v_and_b32_e32 v70, 0xfe000, v70
	v_mov_b32_e32 v71, v99
	v_lshl_add_u64 v[68:69], v[68:69], 0, v[70:71]
	v_lshlrev_b32_e32 v70, 1, v214
	v_lshl_add_u64 v[68:69], v[68:69], 0, v[70:71]
	v_mul_f32_e32 v70, v50, v124
	v_cvt_pk_bf16_f32 v72, v70, s0
	v_lshlrev_b32_e32 v70, 1, v102
	v_lshl_add_u64 v[68:69], v[68:69], 0, v[70:71]
	v_mul_f32_e32 v70, v51, v124
	v_cvt_pk_bf16_f32 v70, v70, s0
	global_store_short v[68:69], v70, off offset:128
	v_mul_f32_e32 v70, v52, v124
	v_cvt_pk_bf16_f32 v70, v70, s0
	global_store_short v[68:69], v70, off offset:256
	v_mul_f32_e32 v70, v53, v124
	v_cvt_pk_bf16_f32 v70, v70, s0
	global_store_short v[68:69], v70, off offset:384
	v_mul_f32_e32 v70, v54, v124
	v_cvt_pk_bf16_f32 v70, v70, s0
	global_store_short v[68:69], v70, off offset:1024
	v_mul_f32_e32 v70, v55, v124
	v_cvt_pk_bf16_f32 v70, v70, s0
	global_store_short v[68:69], v70, off offset:1152
	v_mul_f32_e32 v70, v56, v124
	v_cvt_pk_bf16_f32 v70, v70, s0
	global_store_short v[68:69], v70, off offset:1280
	v_mul_f32_e32 v70, v57, v124
	v_cvt_pk_bf16_f32 v70, v70, s0
	global_store_short v[68:69], v70, off offset:1408
	v_mul_f32_e32 v70, v58, v124
	v_cvt_pk_bf16_f32 v70, v70, s0
	global_store_short v[68:69], v70, off offset:2048
	v_mul_f32_e32 v70, v59, v124
	v_cvt_pk_bf16_f32 v70, v70, s0
	global_store_short v[68:69], v70, off offset:2176
	v_mul_f32_e32 v70, v60, v124
	v_cvt_pk_bf16_f32 v70, v70, s0
	global_store_short v[68:69], v70, off offset:2304
	v_mul_f32_e32 v70, v61, v124
	v_cvt_pk_bf16_f32 v70, v70, s0
	global_store_short v[68:69], v70, off offset:2432
	v_mul_f32_e32 v70, v62, v124
	v_cvt_pk_bf16_f32 v70, v70, s0
	global_store_short v[68:69], v70, off offset:3072
	v_mul_f32_e32 v70, v63, v124
	v_cvt_pk_bf16_f32 v70, v70, s0
	global_store_short v[68:69], v70, off offset:3200
	v_mul_f32_e32 v70, v64, v124
	v_cvt_pk_bf16_f32 v70, v70, s0
	global_store_short v[68:69], v70, off offset:3328
	v_mul_f32_e32 v70, v65, v124
	v_cvt_pk_bf16_f32 v70, v70, s0
	global_store_short v[68:69], v72, off
	global_store_short v[68:69], v70, off offset:3456
	v_mul_f32_e32 v70, v34, v124
	v_add_co_u32_e32 v68, vcc, s13, v68
	v_cvt_pk_bf16_f32 v70, v70, s0
	s_nop 0
	v_addc_co_u32_e32 v69, vcc, 0, v69, vcc
	global_store_short v[68:69], v70, off
	v_mul_f32_e32 v70, v35, v124
	v_cvt_pk_bf16_f32 v70, v70, s0
	global_store_short v[68:69], v70, off offset:128
	v_mul_f32_e32 v70, v36, v124
	v_cvt_pk_bf16_f32 v70, v70, s0
	global_store_short v[68:69], v70, off offset:256
	v_mul_f32_e32 v70, v37, v124
	v_cvt_pk_bf16_f32 v70, v70, s0
	global_store_short v[68:69], v70, off offset:384
	v_mul_f32_e32 v70, v38, v124
	v_cvt_pk_bf16_f32 v70, v70, s0
	global_store_short v[68:69], v70, off offset:1024
	v_mul_f32_e32 v70, v39, v124
	v_cvt_pk_bf16_f32 v70, v70, s0
	global_store_short v[68:69], v70, off offset:1152
	v_mul_f32_e32 v70, v40, v124
	v_cvt_pk_bf16_f32 v70, v70, s0
	global_store_short v[68:69], v70, off offset:1280
	v_mul_f32_e32 v70, v41, v124
	v_cvt_pk_bf16_f32 v70, v70, s0
	global_store_short v[68:69], v70, off offset:1408
	v_mul_f32_e32 v70, v42, v124
	v_cvt_pk_bf16_f32 v70, v70, s0
	global_store_short v[68:69], v70, off offset:2048
	v_mul_f32_e32 v70, v43, v124
	v_cvt_pk_bf16_f32 v70, v70, s0
	global_store_short v[68:69], v70, off offset:2176
	v_mul_f32_e32 v70, v44, v124
	v_cvt_pk_bf16_f32 v70, v70, s0
	global_store_short v[68:69], v70, off offset:2304
	v_mul_f32_e32 v70, v45, v124
	v_cvt_pk_bf16_f32 v70, v70, s0
	global_store_short v[68:69], v70, off offset:2432
	v_mul_f32_e32 v70, v46, v124
	v_cvt_pk_bf16_f32 v70, v70, s0
	global_store_short v[68:69], v70, off offset:3072
	v_mul_f32_e32 v70, v47, v124
	v_cvt_pk_bf16_f32 v70, v70, s0
	global_store_short v[68:69], v70, off offset:3200
	v_mul_f32_e32 v70, v48, v124
	v_cvt_pk_bf16_f32 v70, v70, s0
	global_store_short v[68:69], v70, off offset:3328
	v_mul_f32_e32 v70, v49, v124
	v_cvt_pk_bf16_f32 v70, v70, s0
	global_store_short v[68:69], v70, off offset:3456

.LBB0_903:
	s_mov_b64 s[4:5], 0
	s_cbranch_execz .LBB0_905
	v_lshlrev_b32_e32 v35, 7, v71
	v_lshl_add_u64 v[36:37], s[52:53], 0, v[98:99]
	v_and_b32_e32 v38, 0xfe000, v35
	v_mov_b32_e32 v39, v99
	v_lshl_add_u64 v[36:37], v[36:37], 0, v[38:39]
	v_lshlrev_b32_e32 v38, 1, v215
	v_lshl_add_u64 v[36:37], v[36:37], 0, v[38:39]
	v_mul_f32_e32 v35, v18, v70
	v_lshlrev_b32_e32 v38, 1, v102
	v_cvt_pk_bf16_f32 v35, v35, s0
	v_lshl_add_u64 v[36:37], v[36:37], 0, v[38:39]
	global_store_short v[36:37], v35, off
	v_mul_f32_e32 v35, v19, v70
	v_cvt_pk_bf16_f32 v35, v35, s0
	global_store_short v[36:37], v35, off offset:128
	v_mul_f32_e32 v35, v20, v70
	v_cvt_pk_bf16_f32 v35, v35, s0
	global_store_short v[36:37], v35, off offset:256
	v_mul_f32_e32 v35, v21, v70
	v_cvt_pk_bf16_f32 v35, v35, s0
	global_store_short v[36:37], v35, off offset:384
	v_mul_f32_e32 v35, v22, v70
	v_cvt_pk_bf16_f32 v35, v35, s0
	global_store_short v[36:37], v35, off offset:1024
	v_mul_f32_e32 v35, v23, v70
	v_cvt_pk_bf16_f32 v35, v35, s0
	global_store_short v[36:37], v35, off offset:1152
	v_mul_f32_e32 v35, v24, v70
	v_cvt_pk_bf16_f32 v35, v35, s0
	global_store_short v[36:37], v35, off offset:1280
	v_mul_f32_e32 v35, v25, v70
	v_cvt_pk_bf16_f32 v35, v35, s0
	global_store_short v[36:37], v35, off offset:1408
	v_mul_f32_e32 v35, v26, v70
	v_cvt_pk_bf16_f32 v35, v35, s0
	global_store_short v[36:37], v35, off offset:2048
	v_mul_f32_e32 v35, v27, v70
	v_cvt_pk_bf16_f32 v35, v35, s0
	global_store_short v[36:37], v35, off offset:2176
	v_mul_f32_e32 v35, v28, v70
	v_cvt_pk_bf16_f32 v35, v35, s0
	global_store_short v[36:37], v35, off offset:2304
	v_mul_f32_e32 v35, v29, v70
	v_cvt_pk_bf16_f32 v35, v35, s0
	global_store_short v[36:37], v35, off offset:2432
	v_mul_f32_e32 v35, v30, v70
	v_cvt_pk_bf16_f32 v35, v35, s0
	global_store_short v[36:37], v35, off offset:3072
	v_mul_f32_e32 v35, v31, v70
	v_cvt_pk_bf16_f32 v35, v35, s0
	global_store_short v[36:37], v35, off offset:3200
	v_mul_f32_e32 v35, v32, v70
	v_cvt_pk_bf16_f32 v35, v35, s0
	global_store_short v[36:37], v35, off offset:3328
	v_mul_f32_e32 v35, v33, v70
	v_cvt_pk_bf16_f32 v35, v35, s0
	global_store_short v[36:37], v35, off offset:3456
	v_mul_f32_e32 v35, v2, v70
	v_add_co_u32_e32 v36, vcc, s13, v36
	v_cvt_pk_bf16_f32 v35, v35, s0
	s_nop 0
	v_addc_co_u32_e32 v37, vcc, 0, v37, vcc
	global_store_short v[36:37], v35, off
	v_mul_f32_e32 v35, v3, v70
	v_cvt_pk_bf16_f32 v35, v35, s0
	global_store_short v[36:37], v35, off offset:128
	v_mul_f32_e32 v35, v4, v70
	v_cvt_pk_bf16_f32 v35, v35, s0
	global_store_short v[36:37], v35, off offset:256
	v_mul_f32_e32 v35, v5, v70
	v_cvt_pk_bf16_f32 v35, v35, s0
	global_store_short v[36:37], v35, off offset:384
	v_mul_f32_e32 v35, v6, v70
	v_cvt_pk_bf16_f32 v35, v35, s0
	global_store_short v[36:37], v35, off offset:1024
	v_mul_f32_e32 v35, v7, v70
	v_cvt_pk_bf16_f32 v35, v35, s0
	global_store_short v[36:37], v35, off offset:1152
	v_mul_f32_e32 v35, v8, v70
	v_cvt_pk_bf16_f32 v35, v35, s0
	global_store_short v[36:37], v35, off offset:1280
	v_mul_f32_e32 v35, v9, v70
	v_cvt_pk_bf16_f32 v35, v35, s0
	global_store_short v[36:37], v35, off offset:1408
	v_mul_f32_e32 v35, v10, v70
	v_cvt_pk_bf16_f32 v35, v35, s0
	global_store_short v[36:37], v35, off offset:2048
	v_mul_f32_e32 v35, v11, v70
	v_cvt_pk_bf16_f32 v35, v35, s0
	global_store_short v[36:37], v35, off offset:2176
	v_mul_f32_e32 v35, v12, v70
	v_cvt_pk_bf16_f32 v35, v35, s0
	global_store_short v[36:37], v35, off offset:2304
	v_mul_f32_e32 v35, v13, v70
	v_cvt_pk_bf16_f32 v35, v35, s0
	global_store_short v[36:37], v35, off offset:2432
	v_mul_f32_e32 v35, v14, v70
	v_cvt_pk_bf16_f32 v35, v35, s0
	global_store_short v[36:37], v35, off offset:3072
	v_mul_f32_e32 v35, v15, v70
	v_cvt_pk_bf16_f32 v35, v35, s0
	global_store_short v[36:37], v35, off offset:3200
	v_mul_f32_e32 v35, v16, v70
	v_cvt_pk_bf16_f32 v35, v35, s0
	global_store_short v[36:37], v35, off offset:3328
	v_mul_f32_e32 v35, v17, v70
	v_cvt_pk_bf16_f32 v35, v35, s0
	global_store_short v[36:37], v35, off offset:3456

.LBB0_2164:
	s_or_b64 exec, exec, s[20:21]
	v_add_u32_e32 v38, v34, v35
	v_bcnt_u32_b32 v37, v37, 0
	v_add_u32_e32 v38, v38, v36
	v_add_u32_e32 v150, v38, v37
	v_mul_f32_e32 v38, v133, v146
	v_cmp_eq_u32_e32 vcc, 0, v150
	v_pk_mul_f32 v[82:83], v[38:39], v[18:19] op_sel_hi:[0,1]
	v_add_u32_e32 v215, 0x9000, v214
	v_pk_mul_f32 v[84:85], v[38:39], v[20:21] op_sel_hi:[0,1]
	v_add_u32_e32 v216, 0x9008, v214
	v_pk_mul_f32 v[86:87], v[38:39], v[22:23] op_sel_hi:[0,1]
	v_add_u32_e32 v217, 0x9020, v214
	v_pk_mul_f32 v[88:89], v[38:39], v[24:25] op_sel_hi:[0,1]
	v_add_u32_e32 v218, 0x9028, v214
	v_pk_mul_f32 v[90:91], v[38:39], v[26:27] op_sel_hi:[0,1]
	v_add_u32_e32 v219, 0x9040, v214
	v_pk_mul_f32 v[92:93], v[38:39], v[28:29] op_sel_hi:[0,1]
	v_add_u32_e32 v220, 0x9048, v214
	v_pk_mul_f32 v[94:95], v[38:39], v[30:31] op_sel_hi:[0,1]
	v_add_u32_e32 v221, 0x9060, v214
	v_pk_mul_f32 v[96:97], v[38:39], v[32:33] op_sel_hi:[0,1]
	v_add_u32_e32 v222, 0x9068, v214
	v_pk_mul_f32 v[134:135], v[38:39], v[2:3] op_sel_hi:[0,1]
	v_add_u32_e32 v223, 0x9080, v214
	v_pk_mul_f32 v[136:137], v[38:39], v[4:5] op_sel_hi:[0,1]
	v_add_u32_e32 v224, 0x9088, v214
	v_pk_mul_f32 v[138:139], v[38:39], v[6:7] op_sel_hi:[0,1]
	v_add_u32_e32 v225, 0x90a0, v214
	v_pk_mul_f32 v[140:141], v[38:39], v[8:9] op_sel_hi:[0,1]
	v_add_u32_e32 v226, 0x90a8, v214
	v_pk_mul_f32 v[142:143], v[38:39], v[10:11] op_sel_hi:[0,1]
	v_add_u32_e32 v227, 0x90c0, v214
	v_pk_mul_f32 v[144:145], v[38:39], v[12:13] op_sel_hi:[0,1]
	v_add_u32_e32 v228, 0x90c8, v214
	v_pk_mul_f32 v[146:147], v[38:39], v[14:15] op_sel_hi:[0,1]
	v_add_u32_e32 v229, 0x90e0, v214
	v_pk_mul_f32 v[148:149], v[38:39], v[16:17] op_sel_hi:[0,1]
	v_add_u32_e32 v230, 0x90e8, v214
	s_and_b64 vcc, exec, vcc
	s_lshl_b32 s24, s71, 19
	s_waitcnt lgkmcnt(0)
	s_barrier
	ds_write2_b32 v215, v82, v83 offset1:1
	ds_write2_b32 v216, v84, v85 offset1:1
	ds_write2_b32 v217, v86, v87 offset1:1
	ds_write2_b32 v218, v88, v89 offset1:1
	ds_write2_b32 v219, v90, v91 offset1:1
	ds_write2_b32 v220, v92, v93 offset1:1
	ds_write2_b32 v221, v94, v95 offset1:1
	ds_write2_b32 v222, v96, v97 offset1:1
	ds_write2_b32 v223, v134, v135 offset1:1
	ds_write2_b32 v224, v136, v137 offset1:1
	ds_write2_b32 v225, v138, v139 offset1:1
	ds_write2_b32 v226, v140, v141 offset1:1
	ds_write2_b32 v227, v142, v143 offset1:1
	ds_write2_b32 v228, v144, v145 offset1:1
	ds_write2_b32 v229, v146, v147 offset1:1
	ds_write2_b32 v230, v148, v149 offset1:1
	s_cbranch_vccnz .LBB0_2181
	s_lshl_b32 s96, s66, 12
	s_and_b32 s96, s96, 0x6000
	s_lshl_b32 s95, s66, 3
	s_and_b32 s95, s95, 8
	s_sub_i32 s94, 0x1ff0, s70
	s_mov_b32 s86, 0xff00ff00
	s_mov_b32 s87, 0xff00ff00
	s_mov_b32 s98, 0x1000
	s_mov_b32 s99, 0
	v_and_b32_e32 v40, 15, v166
	v_bfe_u32 v41, v166, 4, 2
	v_lshrrev_b32_e32 v42, 6, v166
	v_mul_u32_u24_e32 v234, 0x90, v40
	v_lshl_add_u32 v234, v41, 4, v234
	v_bfe_u32 v43, v166, 3, 1
	v_lshl_add_u32 v43, v42, 2, v43
	v_add_u32_e32 v236, s94, v43
	v_lshlrev_b32_e32 v44, 2, v41
	v_sub_u32_e32 v239, v236, v44
	v_lshl_add_u32 v45, v42, 5, v40
	v_mul_u32_u24_e32 v45, 0x41, v45
	v_lshl_add_u32 v45, v41, 2, v45
	v_lshlrev_b32_e32 v45, 2, v45
	v_add_u32_e32 v237, 0x9000, v45
	v_add_u32_e32 v238, 0x1040, v237
	v_add_u32_e32 v46, s96, v236
	v_mov_b32_e32 v47, 0
	v_lshlrev_b64 v[46:47], 11, v[46:47]
	v_lshl_add_u64 v[46:47], s[42:43], 0, v[46:47]
	v_and_b32_e32 v48, 7, v166
	v_or_b32_e32 v48, s95, v48
	v_lshlrev_b32_e32 v48, 7, v48
	v_lshl_add_u32 v48, v41, 4, v48
	v_mov_b32_e32 v49, 0
	v_lshl_add_u64 v[46:47], v[46:47], 0, v[48:49]
	global_load_dwordx4 v[66:69], v[46:47], off
	global_load_dwordx4 v[70:73], v[46:47], off offset:64
	v_lshl_add_u64 v[48:49], v[46:47], 0, s[98:99]
	global_load_dwordx4 v[74:77], v[48:49], off
	global_load_dwordx4 v[78:81], v[48:49], off offset:64
	v_mov_b32_e32 v235, 0
	ds_read_b32 v2, v211
	s_lshl_b32 s22, s24, 1
	v_readlane_b32 s20, v231, 14
	s_add_u32 s20, s20, s22
	v_readlane_b32 s21, v231, 10
	s_addc_u32 s21, s21, 0
	s_waitcnt lgkmcnt(0)
	v_ashrrev_i32_e32 v3, 31, v2
	s_add_u32 s22, s52, s22
	v_lshlrev_b64 v[2:3], 13, v[2:3]
	s_addc_u32 s23, s53, 0
	v_lshl_add_u64 v[4:5], s[20:21], 0, v[2:3]
	v_mov_b32_e32 v129, v105
	v_lshl_add_u64 v[2:3], s[22:23], 0, v[2:3]
	v_lshl_add_u64 v[4:5], v[4:5], 0, v[128:129]
	v_lshl_add_u64 v[6:7], v[4:5], 0, v[106:107]
	v_lshl_add_u64 v[2:3], v[2:3], 0, v[128:129]
	v_lshl_add_u64 v[4:5], v[4:5], 0, v[108:109]
	v_lshl_add_u64 v[8:9], v[2:3], 0, v[106:107]
	global_load_dwordx4 v[82:85], v[6:7], off
	global_load_dwordx4 v[86:89], v[8:9], off
	v_lshl_add_u64 v[2:3], v[2:3], 0, v[108:109]
	global_load_dwordx4 v[90:93], v[4:5], off
	global_load_dwordx4 v[94:97], v[2:3], off
	v_cmp_eq_u32_e32 vcc, 1, v150
	s_and_b64 vcc, exec, vcc
	s_waitcnt vmcnt(3)
	ds_write_b128 v153, v[82:85]
	s_waitcnt vmcnt(2)
	ds_write_b128 v153, v[86:89] offset:9216
	s_waitcnt vmcnt(1)
	ds_write_b128 v155, v[90:93]
	s_waitcnt vmcnt(0)
	ds_write_b128 v155, v[94:97] offset:9216
	s_cbranch_vccnz .LBB0_2167
	ds_read_b32 v2, v212
	s_waitcnt lgkmcnt(0)
	v_ashrrev_i32_e32 v3, 31, v2
	v_lshlrev_b64 v[2:3], 13, v[2:3]
	v_lshl_add_u64 v[4:5], s[20:21], 0, v[2:3]
	v_lshl_add_u64 v[2:3], s[22:23], 0, v[2:3]
	v_lshl_add_u64 v[4:5], v[4:5], 0, v[128:129]
	v_lshl_add_u64 v[2:3], v[2:3], 0, v[128:129]
	v_lshl_add_u64 v[6:7], v[4:5], 0, v[106:107]
	v_lshl_add_u64 v[4:5], v[4:5], 0, v[108:109]
	v_lshl_add_u64 v[8:9], v[2:3], 0, v[106:107]
	global_load_dwordx4 v[82:85], v[6:7], off
	global_load_dwordx4 v[86:89], v[8:9], off
	v_lshl_add_u64 v[2:3], v[2:3], 0, v[108:109]
	global_load_dwordx4 v[90:93], v[4:5], off
	global_load_dwordx4 v[94:97], v[2:3], off

.LBB0_2172:
	v_mov_b32_e32 v34, s25
	ds_read_b32 v138, v34
	s_waitcnt lgkmcnt(0)
	v_readfirstlane_b32 s76, v138
	s_lshr_b32 s77, s76, 5
	s_lshl_b32 s77, s77, 2
	s_and_b32 s78, s76, 31
	v_add_u32_e32 v35, s77, v168
	v_add_u32_e32 v35, 0x11200, v35
	ds_read2_b32 v[36:37], v35 offset1:4
	ds_read2_b32 v[38:39], v35 offset0:8 offset1:12
	s_waitcnt lgkmcnt(0)
	v_or_b32_e32 v34, v36, v37
	v_or_b32_e32 v35, v38, v39
	s_nop 0
	v_readfirstlane_b32 s79, v34
	v_readfirstlane_b32 s80, v35
	s_bitcmp1_b32 s79, s78
	s_cselect_b32 s81, 1, 0
	s_bitcmp1_b32 s80, s78
	s_cselect_b32 s82, 1, 0
	s_or_b32 s83, s81, s82
	s_cmp_eq_u32 s83, 0
	s_cbranch_scc1 .LBB0_2178
	s_mulk_i32 s21, 0x4800
	v_add_u32_e32 v149, s21, v234
	s_lshl_b32 s83, s76, 6
	v_subrev_u32_e32 v147, s83, v239
	v_cndmask_b32_e64 v146, v36, v37, s[86:87]
	v_cndmask_b32_e64 v151, v38, v39, s[86:87]
	v_lshrrev_b32_e32 v146, s78, v146
	v_lshrrev_b32_e32 v151, s78, v151
	v_and_b32_e32 v146, 1, v146
	v_and_b32_e32 v151, 1, v151
	v_cmp_ne_u32_e32 vcc, 0, v146
	s_cmp_eq_u32 s81, 0
	s_nop 0
	v_cndmask_b32_e32 v146, v213, v100, vcc
	s_cbranch_scc1 .Lsb16_g1_0
	ds_read_b128 v[50:53], v149
	ds_read_b128 v[54:57], v149 offset:64
	ds_read_b128 v[58:61], v149 offset:2304
	ds_read_b128 v[62:65], v149 offset:2368
	s_waitcnt lgkmcnt(3)
	v_mfma_f32_16x16x32_bf16 v[34:37], v[50:53], v[66:69], 0
	s_waitcnt lgkmcnt(2)
	v_mfma_f32_16x16x32_bf16 v[34:37], v[54:57], v[70:73], v[34:37]
	ds_read_b128 v[50:53], v149 offset:4608
	ds_read_b128 v[54:57], v149 offset:4672
	s_waitcnt lgkmcnt(3)
	v_mfma_f32_16x16x32_bf16 v[38:41], v[58:61], v[66:69], 0
	s_waitcnt lgkmcnt(2)
	v_mfma_f32_16x16x32_bf16 v[38:41], v[62:65], v[70:73], v[38:41]
	ds_read_b128 v[58:61], v149 offset:6912
	ds_read_b128 v[62:65], v149 offset:6976
	s_waitcnt lgkmcnt(3)
	v_mfma_f32_16x16x32_bf16 v[42:45], v[50:53], v[66:69], 0
	s_waitcnt lgkmcnt(2)
	v_mfma_f32_16x16x32_bf16 v[42:45], v[54:57], v[70:73], v[42:45]
	s_waitcnt lgkmcnt(1)
	v_mfma_f32_16x16x32_bf16 v[46:49], v[58:61], v[66:69], 0
	s_waitcnt lgkmcnt(0)
	v_mfma_f32_16x16x32_bf16 v[46:49], v[62:65], v[70:73], v[46:49]
	ds_read_b128 v[50:53], v149 offset:9216
	ds_read_b128 v[54:57], v149 offset:9280
	ds_read_b128 v[58:61], v149 offset:11520
	ds_read_b128 v[62:65], v149 offset:11584
	v_pk_fma_f32 v[34:35], v[34:35], s[48:49], v[146:147] op_sel_hi:[1,0,0]
	v_pk_fma_f32 v[36:37], v[36:37], s[48:49], v[146:147] op_sel_hi:[1,0,0]
	v_pk_fma_f32 v[38:39], v[38:39], s[48:49], v[146:147] op_sel_hi:[1,0,0]
	v_pk_fma_f32 v[40:41], v[40:41], s[48:49], v[146:147] op_sel_hi:[1,0,0]
	v_pk_fma_f32 v[42:43], v[42:43], s[48:49], v[146:147] op_sel_hi:[1,0,0]
	v_pk_fma_f32 v[44:45], v[44:45], s[48:49], v[146:147] op_sel_hi:[1,0,0]
	v_pk_fma_f32 v[46:47], v[46:47], s[48:49], v[146:147] op_sel_hi:[1,0,0]
	v_pk_fma_f32 v[48:49], v[48:49], s[48:49], v[146:147] op_sel_hi:[1,0,0]
	s_cmp_lg_u32 s76, s72
	s_cbranch_scc1 .Lsb16_nm0_0
	v_cmp_le_i32_e64 s[98:99], 0, v147
	s_nop 1
	v_cndmask_b32_e64 v34, v213, v34, s[98:99]
	v_cmp_le_i32_e64 s[98:99], 1, v147
	s_nop 1
	v_cndmask_b32_e64 v35, v213, v35, s[98:99]
	v_cmp_le_i32_e64 s[98:99], 2, v147
	s_nop 1
	v_cndmask_b32_e64 v36, v213, v36, s[98:99]
	v_cmp_le_i32_e64 s[98:99], 3, v147
	s_nop 1
	v_cndmask_b32_e64 v37, v213, v37, s[98:99]
	v_cmp_le_i32_e64 s[98:99], 16, v147
	s_nop 1
	v_cndmask_b32_e64 v38, v213, v38, s[98:99]
	v_cmp_le_i32_e64 s[98:99], 17, v147
	s_nop 1
	v_cndmask_b32_e64 v39, v213, v39, s[98:99]
	v_cmp_le_i32_e64 s[98:99], 18, v147
	s_nop 1
	v_cndmask_b32_e64 v40, v213, v40, s[98:99]
	v_cmp_le_i32_e64 s[98:99], 19, v147
	s_nop 1
	v_cndmask_b32_e64 v41, v213, v41, s[98:99]
	v_cmp_le_i32_e64 s[98:99], 32, v147
	s_nop 1
	v_cndmask_b32_e64 v42, v213, v42, s[98:99]
	v_cmp_le_i32_e64 s[98:99], 33, v147
	s_nop 1
	v_cndmask_b32_e64 v43, v213, v43, s[98:99]
	v_cmp_le_i32_e64 s[98:99], 34, v147
	s_nop 1
	v_cndmask_b32_e64 v44, v213, v44, s[98:99]
	v_cmp_le_i32_e64 s[98:99], 35, v147
	s_nop 1
	v_cndmask_b32_e64 v45, v213, v45, s[98:99]
	v_cmp_le_i32_e64 s[98:99], 48, v147
	s_nop 1
	v_cndmask_b32_e64 v46, v213, v46, s[98:99]
	v_cmp_le_i32_e64 s[98:99], 49, v147
	s_nop 1
	v_cndmask_b32_e64 v47, v213, v47, s[98:99]
	v_cmp_le_i32_e64 s[98:99], 50, v147
	s_nop 1
	v_cndmask_b32_e64 v48, v213, v48, s[98:99]
	v_cmp_le_i32_e64 s[98:99], 51, v147
	s_nop 1
	v_cndmask_b32_e64 v49, v213, v49, s[98:99]
.Lsb16_nm0_0:
	v_exp_f32_e32 v34, v34
	v_exp_f32_e32 v35, v35
	v_exp_f32_e32 v36, v36
	v_exp_f32_e32 v37, v37
	v_exp_f32_e32 v38, v38
	v_exp_f32_e32 v39, v39
	v_exp_f32_e32 v40, v40
	v_exp_f32_e32 v41, v41
	v_exp_f32_e32 v42, v42
	v_exp_f32_e32 v43, v43
	v_exp_f32_e32 v44, v44
	v_exp_f32_e32 v45, v45
	v_exp_f32_e32 v46, v46
	v_exp_f32_e32 v47, v47
	v_exp_f32_e32 v48, v48
	v_exp_f32_e32 v49, v49
	v_pk_add_f32 v[138:139], v[34:35], v[36:37]
	v_pk_add_f32 v[140:141], v[38:39], v[40:41]
	v_pk_add_f32 v[142:143], v[42:43], v[44:45]
	v_pk_add_f32 v[144:145], v[46:47], v[48:49]
	v_pk_add_f32 v[138:139], v[138:139], v[140:141]
	v_pk_add_f32 v[142:143], v[142:143], v[144:145]
	v_pk_add_f32 v[138:139], v[138:139], v[142:143]
	v_add_f32_e32 v140, v138, v139
	v_add_f32_e32 v129, v129, v140
	v_cvt_pk_bf16_f32 v138, v34, v35
	v_cvt_pk_bf16_f32 v139, v36, v37
	v_cvt_pk_bf16_f32 v140, v38, v39
	v_cvt_pk_bf16_f32 v141, v40, v41
	v_cvt_pk_bf16_f32 v142, v42, v43
	v_cvt_pk_bf16_f32 v143, v44, v45
	v_cvt_pk_bf16_f32 v144, v46, v47
	v_cvt_pk_bf16_f32 v145, v48, v49
	s_waitcnt lgkmcnt(3)
	v_mfma_f32_16x16x32_bf16 v[2:5], v[50:53], v[138:141], v[2:5]
	s_waitcnt lgkmcnt(2)
	v_mfma_f32_16x16x32_bf16 v[2:5], v[54:57], v[142:145], v[2:5]
	ds_read_b128 v[50:53], v149 offset:13824
	ds_read_b128 v[54:57], v149 offset:13888
	s_waitcnt lgkmcnt(3)
	v_mfma_f32_16x16x32_bf16 v[6:9], v[58:61], v[138:141], v[6:9]
	s_waitcnt lgkmcnt(2)
	v_mfma_f32_16x16x32_bf16 v[6:9], v[62:65], v[142:145], v[6:9]
	ds_read_b128 v[58:61], v149 offset:16128
	ds_read_b128 v[62:65], v149 offset:16192
	s_waitcnt lgkmcnt(3)
	v_mfma_f32_16x16x32_bf16 v[10:13], v[50:53], v[138:141], v[10:13]
	s_waitcnt lgkmcnt(2)
	v_mfma_f32_16x16x32_bf16 v[10:13], v[54:57], v[142:145], v[10:13]
	s_waitcnt lgkmcnt(1)
	v_mfma_f32_16x16x32_bf16 v[14:17], v[58:61], v[138:141], v[14:17]
	s_waitcnt lgkmcnt(0)
	v_mfma_f32_16x16x32_bf16 v[14:17], v[62:65], v[142:145], v[14:17]
.Lsb16_g1_0:
	s_cmp_eq_u32 s82, 0
	s_cbranch_scc1 .LBB0_2178
	v_cmp_ne_u32_e32 vcc, 0, v151
	v_add_u32_e32 v147, 2, v147
	ds_read_b128 v[50:53], v149
	ds_read_b128 v[54:57], v149 offset:64
	ds_read_b128 v[58:61], v149 offset:2304
	ds_read_b128 v[62:65], v149 offset:2368
	v_cndmask_b32_e32 v146, v213, v100, vcc
	s_waitcnt lgkmcnt(3)
	v_mfma_f32_16x16x32_bf16 v[34:37], v[50:53], v[74:77], 0
	s_waitcnt lgkmcnt(2)
	v_mfma_f32_16x16x32_bf16 v[34:37], v[54:57], v[78:81], v[34:37]
	ds_read_b128 v[50:53], v149 offset:4608
	ds_read_b128 v[54:57], v149 offset:4672
	s_waitcnt lgkmcnt(3)
	v_mfma_f32_16x16x32_bf16 v[38:41], v[58:61], v[74:77], 0
	s_waitcnt lgkmcnt(2)
	v_mfma_f32_16x16x32_bf16 v[38:41], v[62:65], v[78:81], v[38:41]
	ds_read_b128 v[58:61], v149 offset:6912
	ds_read_b128 v[62:65], v149 offset:6976
	s_waitcnt lgkmcnt(3)
	v_mfma_f32_16x16x32_bf16 v[42:45], v[50:53], v[74:77], 0
	s_waitcnt lgkmcnt(2)
	v_mfma_f32_16x16x32_bf16 v[42:45], v[54:57], v[78:81], v[42:45]
	s_waitcnt lgkmcnt(1)
	v_mfma_f32_16x16x32_bf16 v[46:49], v[58:61], v[74:77], 0
	s_waitcnt lgkmcnt(0)
	v_mfma_f32_16x16x32_bf16 v[46:49], v[62:65], v[78:81], v[46:49]
	ds_read_b128 v[50:53], v149 offset:9216
	ds_read_b128 v[54:57], v149 offset:9280
	ds_read_b128 v[58:61], v149 offset:11520
	ds_read_b128 v[62:65], v149 offset:11584
	v_pk_fma_f32 v[34:35], v[34:35], s[48:49], v[146:147] op_sel_hi:[1,0,0]
	v_pk_fma_f32 v[36:37], v[36:37], s[48:49], v[146:147] op_sel_hi:[1,0,0]
	v_pk_fma_f32 v[38:39], v[38:39], s[48:49], v[146:147] op_sel_hi:[1,0,0]
	v_pk_fma_f32 v[40:41], v[40:41], s[48:49], v[146:147] op_sel_hi:[1,0,0]
	v_pk_fma_f32 v[42:43], v[42:43], s[48:49], v[146:147] op_sel_hi:[1,0,0]
	v_pk_fma_f32 v[44:45], v[44:45], s[48:49], v[146:147] op_sel_hi:[1,0,0]
	v_pk_fma_f32 v[46:47], v[46:47], s[48:49], v[146:147] op_sel_hi:[1,0,0]
	v_pk_fma_f32 v[48:49], v[48:49], s[48:49], v[146:147] op_sel_hi:[1,0,0]
	s_cmp_lg_u32 s76, s72
	s_cbranch_scc1 .Lsb16_nm1_0
	v_cmp_le_i32_e64 s[98:99], 0, v147
	s_nop 1
	v_cndmask_b32_e64 v34, v213, v34, s[98:99]
	v_cmp_le_i32_e64 s[98:99], 1, v147
	s_nop 1
	v_cndmask_b32_e64 v35, v213, v35, s[98:99]
	v_cmp_le_i32_e64 s[98:99], 2, v147
	s_nop 1
	v_cndmask_b32_e64 v36, v213, v36, s[98:99]
	v_cmp_le_i32_e64 s[98:99], 3, v147
	s_nop 1
	v_cndmask_b32_e64 v37, v213, v37, s[98:99]
	v_cmp_le_i32_e64 s[98:99], 16, v147
	s_nop 1
	v_cndmask_b32_e64 v38, v213, v38, s[98:99]
	v_cmp_le_i32_e64 s[98:99], 17, v147
	s_nop 1
	v_cndmask_b32_e64 v39, v213, v39, s[98:99]
	v_cmp_le_i32_e64 s[98:99], 18, v147
	s_nop 1
	v_cndmask_b32_e64 v40, v213, v40, s[98:99]
	v_cmp_le_i32_e64 s[98:99], 19, v147
	s_nop 1
	v_cndmask_b32_e64 v41, v213, v41, s[98:99]
	v_cmp_le_i32_e64 s[98:99], 32, v147
	s_nop 1
	v_cndmask_b32_e64 v42, v213, v42, s[98:99]
	v_cmp_le_i32_e64 s[98:99], 33, v147
	s_nop 1
	v_cndmask_b32_e64 v43, v213, v43, s[98:99]
	v_cmp_le_i32_e64 s[98:99], 34, v147
	s_nop 1
	v_cndmask_b32_e64 v44, v213, v44, s[98:99]
	v_cmp_le_i32_e64 s[98:99], 35, v147
	s_nop 1
	v_cndmask_b32_e64 v45, v213, v45, s[98:99]
	v_cmp_le_i32_e64 s[98:99], 48, v147
	s_nop 1
	v_cndmask_b32_e64 v46, v213, v46, s[98:99]
	v_cmp_le_i32_e64 s[98:99], 49, v147
	s_nop 1
	v_cndmask_b32_e64 v47, v213, v47, s[98:99]
	v_cmp_le_i32_e64 s[98:99], 50, v147
	s_nop 1
	v_cndmask_b32_e64 v48, v213, v48, s[98:99]
	v_cmp_le_i32_e64 s[98:99], 51, v147
	s_nop 1
	v_cndmask_b32_e64 v49, v213, v49, s[98:99]
.Lsb16_nm1_0:
	v_exp_f32_e32 v34, v34
	v_exp_f32_e32 v35, v35
	v_exp_f32_e32 v36, v36
	v_exp_f32_e32 v37, v37
	v_exp_f32_e32 v38, v38
	v_exp_f32_e32 v39, v39
	v_exp_f32_e32 v40, v40
	v_exp_f32_e32 v41, v41
	v_exp_f32_e32 v42, v42
	v_exp_f32_e32 v43, v43
	v_exp_f32_e32 v44, v44
	v_exp_f32_e32 v45, v45
	v_exp_f32_e32 v46, v46
	v_exp_f32_e32 v47, v47
	v_exp_f32_e32 v48, v48
	v_exp_f32_e32 v49, v49
	v_pk_add_f32 v[138:139], v[34:35], v[36:37]
	v_pk_add_f32 v[140:141], v[38:39], v[40:41]
	v_pk_add_f32 v[142:143], v[42:43], v[44:45]
	v_pk_add_f32 v[144:145], v[46:47], v[48:49]
	v_pk_add_f32 v[138:139], v[138:139], v[140:141]
	v_pk_add_f32 v[142:143], v[142:143], v[144:145]
	v_pk_add_f32 v[138:139], v[138:139], v[142:143]
	v_add_f32_e32 v140, v138, v139
	v_add_f32_e32 v235, v235, v140
	v_cvt_pk_bf16_f32 v138, v34, v35
	v_cvt_pk_bf16_f32 v139, v36, v37
	v_cvt_pk_bf16_f32 v140, v38, v39
	v_cvt_pk_bf16_f32 v141, v40, v41
	v_cvt_pk_bf16_f32 v142, v42, v43
	v_cvt_pk_bf16_f32 v143, v44, v45
	v_cvt_pk_bf16_f32 v144, v46, v47
	v_cvt_pk_bf16_f32 v145, v48, v49
	s_waitcnt lgkmcnt(3)
	v_mfma_f32_16x16x32_bf16 v[18:21], v[50:53], v[138:141], v[18:21]
	s_waitcnt lgkmcnt(2)
	v_mfma_f32_16x16x32_bf16 v[18:21], v[54:57], v[142:145], v[18:21]
	ds_read_b128 v[50:53], v149 offset:13824
	ds_read_b128 v[54:57], v149 offset:13888
	s_waitcnt lgkmcnt(3)
	v_mfma_f32_16x16x32_bf16 v[22:25], v[58:61], v[138:141], v[22:25]
	s_waitcnt lgkmcnt(2)
	v_mfma_f32_16x16x32_bf16 v[22:25], v[62:65], v[142:145], v[22:25]
	ds_read_b128 v[58:61], v149 offset:16128
	ds_read_b128 v[62:65], v149 offset:16192
	s_waitcnt lgkmcnt(3)
	v_mfma_f32_16x16x32_bf16 v[26:29], v[50:53], v[138:141], v[26:29]
	s_waitcnt lgkmcnt(2)
	v_mfma_f32_16x16x32_bf16 v[26:29], v[54:57], v[142:145], v[26:29]
	s_waitcnt lgkmcnt(1)
	v_mfma_f32_16x16x32_bf16 v[30:33], v[58:61], v[138:141], v[30:33]
	s_waitcnt lgkmcnt(0)
	v_mfma_f32_16x16x32_bf16 v[30:33], v[62:65], v[142:145], v[30:33]
.LBB0_2178:
	v_cmp_ne_u32_e32 vcc, s28, v148
	s_add_i32 s25, s25, 4
	s_barrier
	s_cbranch_vccz .LBB0_2180
	s_mov_b32 s20, s28
	s_branch .LBB0_2168
.LBB0_2180:
	v_mbcnt_lo_u32_b32 v40, -1, 0
	v_mbcnt_hi_u32_b32 v40, -1, v40
	v_xor_b32_e32 v41, 16, v40
	v_lshlrev_b32_e32 v41, 2, v41
	v_xor_b32_e32 v42, 32, v40
	v_lshlrev_b32_e32 v42, 2, v42
	ds_bpermute_b32 v43, v41, v129
	ds_bpermute_b32 v44, v41, v235
	v_add_u32_e32 v46, s96, v236
	v_mov_b32_e32 v47, 0xc0
	v_mad_u64_u32 v[34:35], s[98:99], v46, v47, v[124:125]
	v_and_b32_e32 v48, 7, v166
	v_or_b32_e32 v48, s95, v48
	v_lshlrev_b32_e32 v48, 2, v48
	v_mov_b32_e32 v49, 0
	v_lshl_add_u64 v[34:35], v[34:35], 0, v[48:49]
	global_load_dword v36, v[34:35], off offset:64
	global_load_dword v37, v[34:35], off offset:448
	s_waitcnt lgkmcnt(0)
	v_add_f32_e32 v129, v129, v43
	v_add_f32_e32 v235, v235, v44
	s_nop 0
	ds_bpermute_b32 v43, v42, v129
	ds_bpermute_b32 v44, v42, v235
	v_add_u32_e32 v46, s96, v132
	v_mov_b32_e32 v47, 0
	v_lshlrev_b64 v[46:47], 11, v[46:47]
	v_lshl_add_u64 v[46:47], s[42:43], 0, v[46:47]
	v_or_b32_e32 v48, s95, v102
	v_lshlrev_b32_e32 v48, 7, v48
	v_lshl_add_u64 v[46:47], v[46:47], 0, v[48:49]
	v_lshl_add_u64 v[46:47], v[46:47], 0, v[122:123]
	global_load_dwordx4 v[66:69], v[46:47], off offset:32
	global_load_dwordx4 v[70:73], v[46:47], off offset:64
	global_load_dwordx4 v[74:77], v[46:47], off offset:96
	global_load_dwordx4 v[78:81], v[46:47], off
	s_waitcnt lgkmcnt(0)
	v_add_f32_e32 v129, v129, v43
	v_add_f32_e32 v235, v235, v44
	s_waitcnt vmcnt(4)
	v_div_scale_f32 v40, s[98:99], v129, v129, v36
	v_rcp_f32_e32 v41, v40
	v_div_scale_f32 v42, vcc, v36, v129, v36
	v_fma_f32 v43, -v40, v41, 1.0
	v_fmac_f32_e32 v41, v43, v41
	v_mul_f32_e32 v43, v42, v41
	v_fma_f32 v38, -v40, v43, v42
	v_fmac_f32_e32 v43, v38, v41
	v_fma_f32 v40, -v40, v43, v42
	v_div_fmas_f32 v40, v40, v41, v43
	v_div_fixup_f32 v38, v40, v129, v36
	v_div_scale_f32 v40, s[98:99], v235, v235, v37
	v_rcp_f32_e32 v41, v40
	v_div_scale_f32 v42, vcc, v37, v235, v37
	v_fma_f32 v43, -v40, v41, 1.0
	v_fmac_f32_e32 v41, v43, v41
	v_mul_f32_e32 v43, v42, v41
	v_fma_f32 v44, -v40, v43, v42
	v_fmac_f32_e32 v43, v44, v41
	v_fma_f32 v40, -v40, v43, v42
	v_div_fmas_f32 v40, v40, v41, v43
	v_div_fixup_f32 v44, v40, v235, v37
	ds_read2_b32 v[50:51], v237 offset0:0 offset1:1
	ds_read2_b32 v[52:53], v237 offset0:2 offset1:3
	ds_read2_b32 v[54:55], v237 offset0:16 offset1:17
	ds_read2_b32 v[56:57], v237 offset0:18 offset1:19
	ds_read2_b32 v[58:59], v237 offset0:32 offset1:33
	ds_read2_b32 v[60:61], v237 offset0:34 offset1:35
	ds_read2_b32 v[62:63], v237 offset0:48 offset1:49
	ds_read2_b32 v[64:65], v237 offset0:50 offset1:51
	s_waitcnt lgkmcnt(7)
	v_pk_fma_f32 v[50:51], v[2:3], v[38:39], v[50:51] op_sel_hi:[1,0,1]
	s_waitcnt lgkmcnt(6)
	v_pk_fma_f32 v[52:53], v[4:5], v[38:39], v[52:53] op_sel_hi:[1,0,1]
	s_waitcnt lgkmcnt(5)
	v_pk_fma_f32 v[54:55], v[6:7], v[38:39], v[54:55] op_sel_hi:[1,0,1]
	s_waitcnt lgkmcnt(4)
	v_pk_fma_f32 v[56:57], v[8:9], v[38:39], v[56:57] op_sel_hi:[1,0,1]
	s_waitcnt lgkmcnt(3)
	v_pk_fma_f32 v[58:59], v[10:11], v[38:39], v[58:59] op_sel_hi:[1,0,1]
	s_waitcnt lgkmcnt(2)
	v_pk_fma_f32 v[60:61], v[12:13], v[38:39], v[60:61] op_sel_hi:[1,0,1]
	s_waitcnt lgkmcnt(1)
	v_pk_fma_f32 v[62:63], v[14:15], v[38:39], v[62:63] op_sel_hi:[1,0,1]
	s_waitcnt lgkmcnt(0)
	v_pk_fma_f32 v[64:65], v[16:17], v[38:39], v[64:65] op_sel_hi:[1,0,1]
	ds_write2_b32 v237, v50, v51 offset0:0 offset1:1
	ds_write2_b32 v237, v52, v53 offset0:2 offset1:3
	ds_write2_b32 v237, v54, v55 offset0:16 offset1:17
	ds_write2_b32 v237, v56, v57 offset0:18 offset1:19
	ds_write2_b32 v237, v58, v59 offset0:32 offset1:33
	ds_write2_b32 v237, v60, v61 offset0:34 offset1:35
	ds_write2_b32 v237, v62, v63 offset0:48 offset1:49
	ds_write2_b32 v237, v64, v65 offset0:50 offset1:51
	ds_read2_b32 v[50:51], v238 offset0:0 offset1:1
	ds_read2_b32 v[52:53], v238 offset0:2 offset1:3
	ds_read2_b32 v[54:55], v238 offset0:16 offset1:17
	ds_read2_b32 v[56:57], v238 offset0:18 offset1:19
	ds_read2_b32 v[58:59], v238 offset0:32 offset1:33
	ds_read2_b32 v[60:61], v238 offset0:34 offset1:35
	ds_read2_b32 v[62:63], v238 offset0:48 offset1:49
	ds_read2_b32 v[64:65], v238 offset0:50 offset1:51
	s_waitcnt lgkmcnt(7)
	v_pk_fma_f32 v[50:51], v[18:19], v[44:45], v[50:51] op_sel_hi:[1,0,1]
	s_waitcnt lgkmcnt(6)
	v_pk_fma_f32 v[52:53], v[20:21], v[44:45], v[52:53] op_sel_hi:[1,0,1]
	s_waitcnt lgkmcnt(5)
	v_pk_fma_f32 v[54:55], v[22:23], v[44:45], v[54:55] op_sel_hi:[1,0,1]
	s_waitcnt lgkmcnt(4)
	v_pk_fma_f32 v[56:57], v[24:25], v[44:45], v[56:57] op_sel_hi:[1,0,1]
	s_waitcnt lgkmcnt(3)
	v_pk_fma_f32 v[58:59], v[26:27], v[44:45], v[58:59] op_sel_hi:[1,0,1]
	s_waitcnt lgkmcnt(2)
	v_pk_fma_f32 v[60:61], v[28:29], v[44:45], v[60:61] op_sel_hi:[1,0,1]
	s_waitcnt lgkmcnt(1)
	v_pk_fma_f32 v[62:63], v[30:31], v[44:45], v[62:63] op_sel_hi:[1,0,1]
	s_waitcnt lgkmcnt(0)
	v_pk_fma_f32 v[64:65], v[32:33], v[44:45], v[64:65] op_sel_hi:[1,0,1]
	ds_write2_b32 v238, v50, v51 offset0:0 offset1:1
	ds_write2_b32 v238, v52, v53 offset0:2 offset1:3
	ds_write2_b32 v238, v54, v55 offset0:16 offset1:17
	ds_write2_b32 v238, v56, v57 offset0:18 offset1:19
	ds_write2_b32 v238, v58, v59 offset0:32 offset1:33
	ds_write2_b32 v238, v60, v61 offset0:34 offset1:35
	ds_write2_b32 v238, v62, v63 offset0:48 offset1:49
	ds_write2_b32 v238, v64, v65 offset0:50 offset1:51
	v_mov_b32_e32 v2, 0
	v_mov_b32_e32 v3, 0
	v_mov_b32_e32 v4, 0
	v_mov_b32_e32 v5, 0
	v_mov_b32_e32 v6, 0
	v_mov_b32_e32 v7, 0
	v_mov_b32_e32 v8, 0
	v_mov_b32_e32 v9, 0
	v_mov_b32_e32 v10, 0
	v_mov_b32_e32 v11, 0
	v_mov_b32_e32 v12, 0
	v_mov_b32_e32 v13, 0
	v_mov_b32_e32 v14, 0
	v_mov_b32_e32 v15, 0
	v_mov_b32_e32 v16, 0
	v_mov_b32_e32 v17, 0
	v_mov_b32_e32 v18, 0
	v_mov_b32_e32 v19, 0
	v_mov_b32_e32 v20, 0
	v_mov_b32_e32 v21, 0
	v_mov_b32_e32 v22, 0
	v_mov_b32_e32 v23, 0
	v_mov_b32_e32 v24, 0
	v_mov_b32_e32 v25, 0
	v_mov_b32_e32 v26, 0
	v_mov_b32_e32 v27, 0
	v_mov_b32_e32 v28, 0
	v_mov_b32_e32 v29, 0
	v_mov_b32_e32 v30, 0
	v_mov_b32_e32 v31, 0
	v_mov_b32_e32 v32, 0
	v_mov_b32_e32 v33, 0
	v_mov_b32_e32 v129, 1.0
	s_waitcnt vmcnt(3)
	ds_read2_b32 v[82:83], v215 offset1:1
	ds_read2_b32 v[84:85], v216 offset1:1
	s_waitcnt vmcnt(2)
	ds_read2_b32 v[86:87], v217 offset1:1
	ds_read2_b32 v[88:89], v218 offset1:1
	s_waitcnt vmcnt(1)
	ds_read2_b32 v[90:91], v219 offset1:1
	ds_read2_b32 v[92:93], v220 offset1:1
	s_waitcnt vmcnt(0)
	ds_read2_b32 v[94:95], v221 offset1:1
	ds_read2_b32 v[96:97], v222 offset1:1
	ds_read2_b32 v[134:135], v223 offset1:1
	ds_read2_b32 v[136:137], v224 offset1:1
	ds_read2_b32 v[138:139], v225 offset1:1
	ds_read2_b32 v[140:141], v226 offset1:1
	ds_read2_b32 v[142:143], v227 offset1:1
	ds_read2_b32 v[144:145], v228 offset1:1
	ds_read2_b32 v[146:147], v229 offset1:1
	ds_read2_b32 v[148:149], v230 offset1:1
	s_branch .LBB0_2182

	.amdhsa_kernel _Z15yoco_megakernel5KArgsii
		.amdhsa_group_segment_fixed_size 73744
		.amdhsa_private_segment_fixed_size 0
		.amdhsa_kernarg_size 512
		.amdhsa_user_sgpr_count 2
		.amdhsa_user_sgpr_dispatch_ptr 0
		.amdhsa_user_sgpr_queue_ptr 0
		.amdhsa_user_sgpr_kernarg_segment_ptr 1
		.amdhsa_user_sgpr_dispatch_id 0
		.amdhsa_user_sgpr_kernarg_preload_length 0
		.amdhsa_user_sgpr_kernarg_preload_offset 0
		.amdhsa_user_sgpr_private_segment_size 0
		.amdhsa_uses_dynamic_stack 0
		.amdhsa_enable_private_segment 0
		.amdhsa_system_sgpr_workgroup_id_x 1
		.amdhsa_system_sgpr_workgroup_id_y 0
		.amdhsa_system_sgpr_workgroup_id_z 0
		.amdhsa_system_sgpr_workgroup_info 0
		.amdhsa_system_vgpr_workitem_id 2
		.amdhsa_next_free_vgpr 240
		.amdhsa_next_free_sgpr 102
		.amdhsa_accum_offset 240
		.amdhsa_reserve_vcc 1
		.amdhsa_float_round_mode_32 0
		.amdhsa_float_round_mode_16_64 0
		.amdhsa_float_denorm_mode_32 3
		.amdhsa_float_denorm_mode_16_64 3
		.amdhsa_dx10_clamp 1
		.amdhsa_ieee_mode 1
		.amdhsa_fp16_overflow 0
		.amdhsa_tg_split 0
		.amdhsa_exception_fp_ieee_invalid_op 0
		.amdhsa_exception_fp_denorm_src 0
		.amdhsa_exception_fp_ieee_div_zero 0
		.amdhsa_exception_fp_ieee_overflow 0
		.amdhsa_exception_fp_ieee_underflow 0
		.amdhsa_exception_fp_ieee_inexact 0
		.amdhsa_exception_int_div_zero 0
	.end_amdhsa_kernel

amdhsa.kernels:
  - .agpr_count:     0
    .args:
      - .offset:         0
        .size:           248
        .value_kind:     by_value
      - .offset:         248
        .size:           4
        .value_kind:     by_value
      - .offset:         252
        .size:           4
        .value_kind:     by_value
      - .offset:         256
        .size:           4
        .value_kind:     hidden_block_count_x
      - .offset:         260
        .size:           4
        .value_kind:     hidden_block_count_y
      - .offset:         264
        .size:           4
        .value_kind:     hidden_block_count_z
      - .offset:         268
        .size:           2
        .value_kind:     hidden_group_size_x
      - .offset:         270
        .size:           2
        .value_kind:     hidden_group_size_y
      - .offset:         272
        .size:           2
        .value_kind:     hidden_group_size_z
      - .offset:         274
        .size:           2
        .value_kind:     hidden_remainder_x
      - .offset:         276
        .size:           2
        .value_kind:     hidden_remainder_y
      - .offset:         278
        .size:           2
        .value_kind:     hidden_remainder_z
      - .offset:         296
        .size:           8
        .value_kind:     hidden_global_offset_x
      - .offset:         304
        .size:           8
        .value_kind:     hidden_global_offset_y
      - .offset:         312
        .size:           8
        .value_kind:     hidden_global_offset_z
      - .offset:         320
        .size:           2
        .value_kind:     hidden_grid_dims
      - .offset:         344
        .size:           8
        .value_kind:     hidden_multigrid_sync_arg
    .group_segment_fixed_size: 73744
    .kernarg_segment_align: 8
    .kernarg_segment_size: 512
    .language:       OpenCL C
    .language_version:
      - 2
      - 0
    .max_flat_workgroup_size: 256
    .name:           _Z15yoco_megakernel5KArgsii
    .private_segment_fixed_size: 0
    .sgpr_count:     108
    .sgpr_spill_count: 38
    .symbol:         _Z15yoco_megakernel5KArgsii.kd
    .uniform_work_group_size: 1
    .uses_dynamic_stack: false
    .vgpr_count:     240
    .vgpr_spill_count: 0
    .wavefront_size: 64
